# baseline (speedup 1.0000x reference)
; __device__ __forceinline__ void prep_phase(const Params& p, char* shm, const int tid) {
;     ...
;       for (int rg = blockIdx.x + gridDim.x * wid; rg < N / 16; rg += gridDim.x * 8) {
;         const u16* wp = Wt + (size_t)(rg * 16 + fr) * 1024 + fq * 8;
;         f32x4 acc = {0.f, 0.f, 0.f, 0.f};
; #pragma unroll 8
;         for (int ks = 0; ks < 32; ++ks) {
;           bf16x8 a = *(const bf16x8*)(wp + ks * 32);
;           bf16x8 bb = *(const bf16x8*)(bl + ks * 64);
;           acc = __builtin_amdgcn_mfma_f32_16x16x32_bf16(a, bb, acc, 0, 0, 0);
;         }
;         *(f32x4*)(out + (size_t)fr * N + rg * 16 + fq * 4) = acc;
;       }
.LBB0_887:
	v_ashrrev_i32_e32 v17, 31, v16
	v_lshlrev_b64 v[2:3], 11, v[16:17]
	v_lshl_add_u64 v[18:19], v[14:15], 0, v[2:3]
	v_mov_b32_e32 v2, 0
	v_mov_b32_e32 v11, v23
	s_mov_b64 s[2:3], 0
	v_mov_b32_e32 v3, v2
	v_mov_b32_e32 v4, v2
	v_mov_b32_e32 v5, v2
	global_load_dwordx4 v[72:75], v[18:19], off
	global_load_dwordx4 v[76:79], v[18:19], off offset:64
	global_load_dwordx4 v[80:83], v[18:19], off offset:128
	global_load_dwordx4 v[84:87], v[18:19], off offset:192
	global_load_dwordx4 v[88:91], v[18:19], off offset:256
	global_load_dwordx4 v[92:95], v[18:19], off offset:320
	global_load_dwordx4 v[96:99], v[18:19], off offset:384
	global_load_dwordx4 v[100:103], v[18:19], off offset:448
	global_load_dwordx4 v[104:107], v[18:19], off offset:512
	global_load_dwordx4 v[108:111], v[18:19], off offset:576
	global_load_dwordx4 v[112:115], v[18:19], off offset:640
	global_load_dwordx4 v[116:119], v[18:19], off offset:704
	global_load_dwordx4 v[120:123], v[18:19], off offset:768
	global_load_dwordx4 v[124:127], v[18:19], off offset:832
	global_load_dwordx4 v[128:131], v[18:19], off offset:896
	global_load_dwordx4 v[132:135], v[18:19], off offset:960
	global_load_dwordx4 v[136:139], v[18:19], off offset:1024
	global_load_dwordx4 v[140:143], v[18:19], off offset:1088
	global_load_dwordx4 v[144:147], v[18:19], off offset:1152
	global_load_dwordx4 v[148:151], v[18:19], off offset:1216
	global_load_dwordx4 v[152:155], v[18:19], off offset:1280
	global_load_dwordx4 v[156:159], v[18:19], off offset:1344
	global_load_dwordx4 v[160:163], v[18:19], off offset:1408
	global_load_dwordx4 v[164:167], v[18:19], off offset:1472
	global_load_dwordx4 v[168:171], v[18:19], off offset:1536
	global_load_dwordx4 v[172:175], v[18:19], off offset:1600
	global_load_dwordx4 v[180:183], v[18:19], off offset:1664
	global_load_dwordx4 v[184:187], v[18:19], off offset:1728
	global_load_dwordx4 v[188:191], v[18:19], off offset:1792
	global_load_dwordx4 v[192:195], v[18:19], off offset:1856
	global_load_dwordx4 v[196:199], v[18:19], off offset:1920
	global_load_dwordx4 v[200:203], v[18:19], off offset:1984
	ds_read_b128 v[28:31], v11
	ds_read_b128 v[32:35], v11 offset:64
	ds_read_b128 v[36:39], v11 offset:128
	ds_read_b128 v[40:43], v11 offset:192
	s_waitcnt vmcnt(31) lgkmcnt(3)
	v_mfma_f32_16x16x32_bf16 v[2:5], v[72:75], v[28:31], v[2:5]
	ds_read_b128 v[28:31], v11 offset:256
	s_waitcnt vmcnt(30) lgkmcnt(3)
	v_mfma_f32_16x16x32_bf16 v[2:5], v[76:79], v[32:35], v[2:5]
	ds_read_b128 v[32:35], v11 offset:320
	s_waitcnt vmcnt(29) lgkmcnt(3)
	v_mfma_f32_16x16x32_bf16 v[2:5], v[80:83], v[36:39], v[2:5]
	ds_read_b128 v[36:39], v11 offset:384
	s_waitcnt vmcnt(28) lgkmcnt(3)
	v_mfma_f32_16x16x32_bf16 v[2:5], v[84:87], v[40:43], v[2:5]
	ds_read_b128 v[40:43], v11 offset:448
	s_waitcnt vmcnt(27) lgkmcnt(3)
	v_mfma_f32_16x16x32_bf16 v[2:5], v[88:91], v[28:31], v[2:5]
	ds_read_b128 v[28:31], v11 offset:512
	s_waitcnt vmcnt(26) lgkmcnt(3)
	v_mfma_f32_16x16x32_bf16 v[2:5], v[92:95], v[32:35], v[2:5]
	ds_read_b128 v[32:35], v11 offset:576
	s_waitcnt vmcnt(25) lgkmcnt(3)
	v_mfma_f32_16x16x32_bf16 v[2:5], v[96:99], v[36:39], v[2:5]
	ds_read_b128 v[36:39], v11 offset:640
	s_waitcnt vmcnt(24) lgkmcnt(3)
	v_mfma_f32_16x16x32_bf16 v[2:5], v[100:103], v[40:43], v[2:5]
	ds_read_b128 v[40:43], v11 offset:704
	s_waitcnt vmcnt(23) lgkmcnt(3)
	v_mfma_f32_16x16x32_bf16 v[2:5], v[104:107], v[28:31], v[2:5]
	ds_read_b128 v[28:31], v11 offset:768
	s_waitcnt vmcnt(22) lgkmcnt(3)
	v_mfma_f32_16x16x32_bf16 v[2:5], v[108:111], v[32:35], v[2:5]
	ds_read_b128 v[32:35], v11 offset:832
	s_waitcnt vmcnt(21) lgkmcnt(3)
	v_mfma_f32_16x16x32_bf16 v[2:5], v[112:115], v[36:39], v[2:5]
	ds_read_b128 v[36:39], v11 offset:896
	s_waitcnt vmcnt(20) lgkmcnt(3)
	v_mfma_f32_16x16x32_bf16 v[2:5], v[116:119], v[40:43], v[2:5]
	ds_read_b128 v[40:43], v11 offset:960
	s_waitcnt vmcnt(19) lgkmcnt(3)
	v_mfma_f32_16x16x32_bf16 v[2:5], v[120:123], v[28:31], v[2:5]
	ds_read_b128 v[28:31], v11 offset:1024
	s_waitcnt vmcnt(18) lgkmcnt(3)
	v_mfma_f32_16x16x32_bf16 v[2:5], v[124:127], v[32:35], v[2:5]
	ds_read_b128 v[32:35], v11 offset:1088
	s_waitcnt vmcnt(17) lgkmcnt(3)
	v_mfma_f32_16x16x32_bf16 v[2:5], v[128:131], v[36:39], v[2:5]
	ds_read_b128 v[36:39], v11 offset:1152
	s_waitcnt vmcnt(16) lgkmcnt(3)
	v_mfma_f32_16x16x32_bf16 v[2:5], v[132:135], v[40:43], v[2:5]
	ds_read_b128 v[40:43], v11 offset:1216
	s_waitcnt vmcnt(15) lgkmcnt(3)
	v_mfma_f32_16x16x32_bf16 v[2:5], v[136:139], v[28:31], v[2:5]
	ds_read_b128 v[28:31], v11 offset:1280
	s_waitcnt vmcnt(14) lgkmcnt(3)
	v_mfma_f32_16x16x32_bf16 v[2:5], v[140:143], v[32:35], v[2:5]
	ds_read_b128 v[32:35], v11 offset:1344
	s_waitcnt vmcnt(13) lgkmcnt(3)
	v_mfma_f32_16x16x32_bf16 v[2:5], v[144:147], v[36:39], v[2:5]
	ds_read_b128 v[36:39], v11 offset:1408
	s_waitcnt vmcnt(12) lgkmcnt(3)
	v_mfma_f32_16x16x32_bf16 v[2:5], v[148:151], v[40:43], v[2:5]
	ds_read_b128 v[40:43], v11 offset:1472
	s_waitcnt vmcnt(11) lgkmcnt(3)
	v_mfma_f32_16x16x32_bf16 v[2:5], v[152:155], v[28:31], v[2:5]
	ds_read_b128 v[28:31], v11 offset:1536
	s_waitcnt vmcnt(10) lgkmcnt(3)
	v_mfma_f32_16x16x32_bf16 v[2:5], v[156:159], v[32:35], v[2:5]
	ds_read_b128 v[32:35], v11 offset:1600
	s_waitcnt vmcnt(9) lgkmcnt(3)
	v_mfma_f32_16x16x32_bf16 v[2:5], v[160:163], v[36:39], v[2:5]
	ds_read_b128 v[36:39], v11 offset:1664
	s_waitcnt vmcnt(8) lgkmcnt(3)
	v_mfma_f32_16x16x32_bf16 v[2:5], v[164:167], v[40:43], v[2:5]
	ds_read_b128 v[40:43], v11 offset:1728
	s_waitcnt vmcnt(7) lgkmcnt(3)
	v_mfma_f32_16x16x32_bf16 v[2:5], v[168:171], v[28:31], v[2:5]
	ds_read_b128 v[28:31], v11 offset:1792
	s_waitcnt vmcnt(6) lgkmcnt(3)
	v_mfma_f32_16x16x32_bf16 v[2:5], v[172:175], v[32:35], v[2:5]
	ds_read_b128 v[32:35], v11 offset:1856
	s_waitcnt vmcnt(5) lgkmcnt(3)
	v_mfma_f32_16x16x32_bf16 v[2:5], v[180:183], v[36:39], v[2:5]
	ds_read_b128 v[36:39], v11 offset:1920
	s_waitcnt vmcnt(4) lgkmcnt(3)
	v_mfma_f32_16x16x32_bf16 v[2:5], v[184:187], v[40:43], v[2:5]
	ds_read_b128 v[40:43], v11 offset:1984
	s_waitcnt vmcnt(3) lgkmcnt(3)
	v_mfma_f32_16x16x32_bf16 v[2:5], v[188:191], v[28:31], v[2:5]
	s_waitcnt vmcnt(2) lgkmcnt(2)
	v_mfma_f32_16x16x32_bf16 v[2:5], v[192:195], v[32:35], v[2:5]
	s_waitcnt vmcnt(1) lgkmcnt(1)
	v_mfma_f32_16x16x32_bf16 v[2:5], v[196:199], v[36:39], v[2:5]
	s_waitcnt vmcnt(0) lgkmcnt(0)
	v_mfma_f32_16x16x32_bf16 v[2:5], v[200:203], v[40:43], v[2:5]
	v_readlane_b32 s2, v253, 16
	v_lshlrev_b32_e32 v18, 4, v0
	v_ashrrev_i32_e32 v19, 31, v18
	v_add_u32_e32 v0, s2, v0
	v_cmp_le_i32_e32 vcc, s14, v0
	v_readlane_b32 s2, v254, 39
	v_lshl_add_u64 v[18:19], v[18:19], 2, v[12:13]
	s_or_b64 s[0:1], vcc, s[0:1]
	v_add_u32_e32 v16, s2, v16
	global_store_dwordx4 v[18:19], v[2:5], off
	s_andn2_b64 exec, exec, s[0:1]
	s_cbranch_execnz .LBB0_887
	s_branch .LBB0_868
